# P5 and P4 sample-row GEMM blocks hand-written the same way (A staged once in LDS, all weight loads in flight)
# speedup vs baseline: 1.0363x; 1.0040x over previous
; #define LAS __attribute__((address_space(3)))
; __device__ __forceinline__ int fresh_tid() { int t = threadIdx.x; asm volatile("" : "+v"(t)); return t; }
; template <class BRow>
; __device__ __forceinline__ void skinny32(LAS float* Cs, const bf16_t* A, int lda, const bf16_t* Bt, int ldb, int NC, int K, const BRow& brow) {
;     const int tid = fresh_tid(), lane = tid & 63, wave = __builtin_amdgcn_readfirstlane(tid >> 6), fr = lane & 15, fq = lane >> 4;
;     const int nct = NC >> 4, ldc = NC + 4;
;     for (int ct = wave; ct < nct; ct += NWAVES) {
;         f32x4 acc0 = {0.f, 0.f, 0.f, 0.f}, acc1 = acc0;
;         const bf16_t* ap = A + (size_t)fr * lda + fq * 8; const bf16_t* bp = Bt + (size_t)(brow(ct) + fr) * ldb + fq * 8;
;         bf16x8 a0[8], a1[8], b[8];
; #pragma unroll
;         for (int i = 0; i < 8; ++i) { a0[i] = *(const bf16x8*)(ap + 32 * i); a1[i] = *(const bf16x8*)(ap + (size_t)16 * lda + 32 * i); b[i] = *(const bf16x8*)(bp + 32 * i); }
; #pragma unroll 1
;         for (int k0 = 0; k0 < K; k0 += 256) {
;             bf16x8 n0[8], n1[8], nb[8];
;             const int kn = (k0 + 256 < K) ? k0 + 256 : k0;
; #pragma unroll
;             for (int i = 0; i < 8; ++i) { n0[i] = *(const bf16x8*)(ap + kn + 32 * i); n1[i] = *(const bf16x8*)(ap + (size_t)16 * lda + kn + 32 * i); nb[i] = *(const bf16x8*)(bp + kn + 32 * i); }
; #pragma unroll
;             for (int i = 0; i < 8; ++i) { acc0 = __builtin_amdgcn_mfma_f32_16x16x32_bf16(b[i], a0[i], acc0, 0, 0, 0); acc1 = __builtin_amdgcn_mfma_f32_16x16x32_bf16(b[i], a1[i], acc1, 0, 0, 0); }
; __global__ void __launch_bounds__(NTHR, 2) hymba_fwd(Params P) {
;     ...
;         skinny32(Cs, YSS + (size_t)(32 * mb) * SW, SW, WGLU, SW, 64, SW, [&](int ct) { return 64 * ns + 16 * ct; });
.LBB0_688:
	v_mov_b32_e32 v0, v208
	s_barrier
	s_lshl_b32 s51, s21, 5
	s_ashr_i32 s50, s21, 4
	s_and_b32 s51, s51, 0x1e0
	s_lshl_b32 s53, s51, 10
	s_add_u32 s72, s4, s53
	s_addc_u32 s73, s5, 0
	v_mov_b32_e32 v0, v208
	v_lshrrev_b32_e32 v1, 4, v0
	v_and_b32_e32 v2, 15, v0
	v_readfirstlane_b32 s52, v0
	v_lshlrev_b32_e32 v6, 4, v2
	v_lshl_add_u32 v6, v1, 10, v6
	s_nop 3
	s_ashr_i32 s52, s52, 6
	global_load_dwordx4 v[32:35], v6, s[72:73]
	global_load_dwordx4 v[36:39], v6, s[72:73] offset:256
	global_load_dwordx4 v[40:43], v6, s[72:73] offset:512
	global_load_dwordx4 v[44:47], v6, s[72:73] offset:768
	v_mul_u32_u24_e32 v7, 1040, v1
	v_lshl_add_u32 v7, v2, 4, v7
	v_add_u32_e32 v7, 0x8000, v7
	s_cmp_gt_i32 s52, 3
	s_cbranch_scc1 .Lmy_sk4_helper
	v_and_b32_e32 v8, 63, v0
	v_and_b32_e32 v9, 15, v8
	v_lshrrev_b32_e32 v10, 4, v8
	v_lshlrev_b32_e32 v3, 4, v10
	v_lshl_add_u32 v3, v9, 10, v3
	v_mul_u32_u24_e32 v4, 1040, v9
	v_lshl_add_u32 v4, v10, 4, v4
	v_add_u32_e32 v4, 0x8000, v4
	v_mul_u32_u24_e32 v5, 0x110, v9
	v_lshl_add_u32 v5, v10, 4, v5
	s_lshl_b32 s53, s52, 6
	v_add_u32_e32 v5, s53, v5
	v_readlane_b32 s14, v255, 16
	v_readlane_b32 s15, v255, 17
	s_lshl_b32 s53, s50, 6
	s_lshl_b32 s62, s52, 4
	s_add_i32 s53, s53, s62
	s_lshl_b32 s53, s53, 10
	s_add_u32 s74, s14, s53
	s_addc_u32 s75, s15, 0
	v_mov_b32_e32 v16, 0
	v_mov_b32_e32 v17, 0
	v_mov_b32_e32 v18, 0
	v_mov_b32_e32 v19, 0
	v_mov_b32_e32 v20, 0
	v_mov_b32_e32 v21, 0
	v_mov_b32_e32 v22, 0
	v_mov_b32_e32 v23, 0
	global_load_dwordx4 v[124:127], v3, s[74:75]
	global_load_dwordx4 v[128:131], v3, s[74:75] offset:64
	global_load_dwordx4 v[132:135], v3, s[74:75] offset:128
	global_load_dwordx4 v[136:139], v3, s[74:75] offset:192
	global_load_dwordx4 v[140:143], v3, s[74:75] offset:256
	global_load_dwordx4 v[144:147], v3, s[74:75] offset:320
	global_load_dwordx4 v[148:151], v3, s[74:75] offset:384
	global_load_dwordx4 v[152:155], v3, s[74:75] offset:448
	global_load_dwordx4 v[156:159], v3, s[74:75] offset:512
	global_load_dwordx4 v[164:167], v3, s[74:75] offset:576
	global_load_dwordx4 v[168:171], v3, s[74:75] offset:640
	global_load_dwordx4 v[172:175], v3, s[74:75] offset:704
	global_load_dwordx4 v[176:179], v3, s[74:75] offset:768
	global_load_dwordx4 v[180:183], v3, s[74:75] offset:832
	global_load_dwordx4 v[184:187], v3, s[74:75] offset:896
	global_load_dwordx4 v[188:191], v3, s[74:75] offset:960
	s_waitcnt vmcnt(16)
	ds_write_b128 v7, v[32:35]
	ds_write_b128 v7, v[36:39] offset:256
	ds_write_b128 v7, v[40:43] offset:512
	ds_write_b128 v7, v[44:47] offset:768
	s_waitcnt lgkmcnt(0)
	s_barrier
	ds_read_b128 v[76:79], v4 offset:0
	ds_read_b128 v[80:83], v4 offset:16640
	ds_read_b128 v[84:87], v4 offset:64
	ds_read_b128 v[88:91], v4 offset:16704
	ds_read_b128 v[92:95], v4 offset:128
	ds_read_b128 v[96:99], v4 offset:16768
	s_waitcnt vmcnt(15) lgkmcnt(4)
	v_mfma_f32_16x16x32_bf16 v[16:19], v[124:127], v[76:79], v[16:19]
	v_mfma_f32_16x16x32_bf16 v[20:23], v[124:127], v[80:83], v[20:23]
	ds_read_b128 v[76:79], v4 offset:192
	ds_read_b128 v[80:83], v4 offset:16832
	s_waitcnt vmcnt(14) lgkmcnt(4)
	v_mfma_f32_16x16x32_bf16 v[16:19], v[128:131], v[84:87], v[16:19]
	v_mfma_f32_16x16x32_bf16 v[20:23], v[128:131], v[88:91], v[20:23]
	ds_read_b128 v[84:87], v4 offset:256
	ds_read_b128 v[88:91], v4 offset:16896
	s_waitcnt vmcnt(13) lgkmcnt(4)
	v_mfma_f32_16x16x32_bf16 v[16:19], v[132:135], v[92:95], v[16:19]
	v_mfma_f32_16x16x32_bf16 v[20:23], v[132:135], v[96:99], v[20:23]
	ds_read_b128 v[92:95], v4 offset:320
	ds_read_b128 v[96:99], v4 offset:16960
	s_waitcnt vmcnt(12) lgkmcnt(4)
	v_mfma_f32_16x16x32_bf16 v[16:19], v[136:139], v[76:79], v[16:19]
	v_mfma_f32_16x16x32_bf16 v[20:23], v[136:139], v[80:83], v[20:23]
	ds_read_b128 v[76:79], v4 offset:384
	ds_read_b128 v[80:83], v4 offset:17024
	s_waitcnt vmcnt(11) lgkmcnt(4)
	v_mfma_f32_16x16x32_bf16 v[16:19], v[140:143], v[84:87], v[16:19]
	v_mfma_f32_16x16x32_bf16 v[20:23], v[140:143], v[88:91], v[20:23]
	ds_read_b128 v[84:87], v4 offset:448
	ds_read_b128 v[88:91], v4 offset:17088
	s_waitcnt vmcnt(10) lgkmcnt(4)
	v_mfma_f32_16x16x32_bf16 v[16:19], v[144:147], v[92:95], v[16:19]
	v_mfma_f32_16x16x32_bf16 v[20:23], v[144:147], v[96:99], v[20:23]
	ds_read_b128 v[92:95], v4 offset:512
	ds_read_b128 v[96:99], v4 offset:17152
	s_waitcnt vmcnt(9) lgkmcnt(4)
	v_mfma_f32_16x16x32_bf16 v[16:19], v[148:151], v[76:79], v[16:19]
	v_mfma_f32_16x16x32_bf16 v[20:23], v[148:151], v[80:83], v[20:23]
	ds_read_b128 v[76:79], v4 offset:576
	ds_read_b128 v[80:83], v4 offset:17216
	s_waitcnt vmcnt(8) lgkmcnt(4)
	v_mfma_f32_16x16x32_bf16 v[16:19], v[152:155], v[84:87], v[16:19]
	v_mfma_f32_16x16x32_bf16 v[20:23], v[152:155], v[88:91], v[20:23]
	ds_read_b128 v[84:87], v4 offset:640
	ds_read_b128 v[88:91], v4 offset:17280
	s_waitcnt vmcnt(7) lgkmcnt(4)
	v_mfma_f32_16x16x32_bf16 v[16:19], v[156:159], v[92:95], v[16:19]
	v_mfma_f32_16x16x32_bf16 v[20:23], v[156:159], v[96:99], v[20:23]
	ds_read_b128 v[92:95], v4 offset:704
	ds_read_b128 v[96:99], v4 offset:17344
	s_waitcnt vmcnt(6) lgkmcnt(4)
	v_mfma_f32_16x16x32_bf16 v[16:19], v[164:167], v[76:79], v[16:19]
	v_mfma_f32_16x16x32_bf16 v[20:23], v[164:167], v[80:83], v[20:23]
	ds_read_b128 v[76:79], v4 offset:768
	ds_read_b128 v[80:83], v4 offset:17408
	s_waitcnt vmcnt(5) lgkmcnt(4)
	v_mfma_f32_16x16x32_bf16 v[16:19], v[168:171], v[84:87], v[16:19]
	v_mfma_f32_16x16x32_bf16 v[20:23], v[168:171], v[88:91], v[20:23]
	ds_read_b128 v[84:87], v4 offset:832
	ds_read_b128 v[88:91], v4 offset:17472
	s_waitcnt vmcnt(4) lgkmcnt(4)
	v_mfma_f32_16x16x32_bf16 v[16:19], v[172:175], v[92:95], v[16:19]
	v_mfma_f32_16x16x32_bf16 v[20:23], v[172:175], v[96:99], v[20:23]
	ds_read_b128 v[92:95], v4 offset:896
	ds_read_b128 v[96:99], v4 offset:17536
	s_waitcnt vmcnt(3) lgkmcnt(4)
	v_mfma_f32_16x16x32_bf16 v[16:19], v[176:179], v[76:79], v[16:19]
	v_mfma_f32_16x16x32_bf16 v[20:23], v[176:179], v[80:83], v[20:23]
	ds_read_b128 v[76:79], v4 offset:960
	ds_read_b128 v[80:83], v4 offset:17600
	s_waitcnt vmcnt(2) lgkmcnt(4)
	v_mfma_f32_16x16x32_bf16 v[16:19], v[180:183], v[84:87], v[16:19]
	v_mfma_f32_16x16x32_bf16 v[20:23], v[180:183], v[88:91], v[20:23]
	s_waitcnt vmcnt(1) lgkmcnt(2)
	v_mfma_f32_16x16x32_bf16 v[16:19], v[184:187], v[92:95], v[16:19]
	v_mfma_f32_16x16x32_bf16 v[20:23], v[184:187], v[96:99], v[20:23]
	s_waitcnt vmcnt(0) lgkmcnt(0)
	v_mfma_f32_16x16x32_bf16 v[16:19], v[188:191], v[76:79], v[16:19]
	v_mfma_f32_16x16x32_bf16 v[20:23], v[188:191], v[80:83], v[20:23]
	s_nop 7
	s_nop 3
	ds_write_b128 v5, v[16:19]
	ds_write_b128 v5, v[20:23] offset:4352
	s_branch .Lmy_sk4_done
; #define LAS __attribute__((address_space(3)))
; template <class BRow>
; __device__ __forceinline__ void skinny32(LAS float* Cs, const bf16_t* A, int lda, const bf16_t* Bt, int ldb, int NC, int K, const BRow& brow) {
;     ...
;     for (int ct = wave; ct < nct; ct += NWAVES) {
;         f32x4 acc0 = {0.f, 0.f, 0.f, 0.f}, acc1 = acc0;
;         const bf16_t* ap = A + (size_t)fr * lda + fq * 8; const bf16_t* bp = Bt + (size_t)(brow(ct) + fr) * ldb + fq * 8;
;         bf16x8 a0[8], a1[8], b[8];
; #pragma unroll
;         for (int i = 0; i < 8; ++i) { a0[i] = *(const bf16x8*)(ap + 32 * i); a1[i] = *(const bf16x8*)(ap + (size_t)16 * lda + 32 * i); b[i] = *(const bf16x8*)(bp + 32 * i); }
; #pragma unroll 1
;         for (int k0 = 0; k0 < K; k0 += 256) {
;             bf16x8 n0[8], n1[8], nb[8];
;             const int kn = (k0 + 256 < K) ? k0 + 256 : k0;
; #pragma unroll
;             for (int i = 0; i < 8; ++i) { n0[i] = *(const bf16x8*)(ap + kn + 32 * i); n1[i] = *(const bf16x8*)(ap + (size_t)16 * lda + kn + 32 * i); nb[i] = *(const bf16x8*)(bp + kn + 32 * i); }
; #pragma unroll
; __global__ void __launch_bounds__(NTHR, 2) hymba_fwd(Params P) {
;     ...
;         skinny32(Cs, YSS + (size_t)(32 * mb) * SW, SW, WGLU, SW, 64, SW, [&](int ct) { return 64 * ns + 16 * ct; });
;         const int tid = fresh_tid();
;         if (tid < 256) { const int row = tid >> 3, ch = tid & 7, col = 64 * ns + 8 * ch, m = PT + 32 * mb + row;
;             const f32x4 c0 = *(const LAS f32x4*)(Cs + row * ldc + 8 * ch) + *(const f32x4*)(P.b_glu + col), c1 = *(const LAS f32x4*)(Cs + row * ldc + 8 * ch + 4) + *(const f32x4*)(P.b_glu + col + 4);
;             const u32x4 ys = *(const u32x4*)(YSS + (size_t)(m - PT) * 512 + col), zs = *(const u32x4*)(ZS + (size_t)m * 512 + col);
;             u32x4 w;
;             w.x = pk2(bflo(ys.x) * sigmoidf_(c0[0]) * bflo(zs.x), bfhi(ys.x) * sigmoidf_(c0[1]) * bfhi(zs.x));
;             w.y = pk2(bflo(ys.y) * sigmoidf_(c0[2]) * bflo(zs.y), bfhi(ys.y) * sigmoidf_(c0[3]) * bfhi(zs.y));
;             w.z = pk2(bflo(ys.z) * sigmoidf_(c1[0]) * bflo(zs.z), bfhi(ys.z) * sigmoidf_(c1[1]) * bfhi(zs.z));
;             w.w = pk2(bflo(ys.w) * sigmoidf_(c1[2]) * bflo(zs.w), bfhi(ys.w) * sigmoidf_(c1[3]) * bfhi(zs.w));
;             *(u32x4*)(MX + (size_t)m * 1024 + col) = w; }
.Lmy_sk4_helper:
	s_waitcnt vmcnt(0)
	ds_write_b128 v7, v[32:35]
	ds_write_b128 v7, v[36:39] offset:256
	ds_write_b128 v7, v[40:43] offset:512
	ds_write_b128 v7, v[44:47] offset:768
	s_waitcnt lgkmcnt(0)
	s_barrier
.Lmy_sk4_done:
.LBB0_693:
	v_mov_b32_e32 v0, v208
	s_waitcnt lgkmcnt(0)
	s_barrier
	s_nop 0
	v_cmp_gt_i32_e32 vcc, s17, v0
	s_and_saveexec_b64 s[62:63], vcc
	s_cbranch_execz .LBB0_687
	v_ashrrev_i32_e32 v1, 3, v0
	v_lshlrev_b32_e32 v0, 3, v0
	v_and_b32_e32 v0, 56, v0
	v_lshl_or_b32 v4, s50, 6, v0
	s_movk_i32 s50, 0x110
	v_add_u32_e32 v2, s51, v1
	v_mul_lo_u32 v1, v1, s50
	v_lshlrev_b32_e32 v0, 2, v0
	v_add3_u32 v5, 0, v1, v0
	v_add_u32_e32 v6, 0x10000, v2
	ds_read_b128 v[0:3], v5
	ds_read_b128 v[8:11], v5 offset:16
	v_ashrrev_i32_e32 v5, 31, v4
	v_lshl_add_u64 v[16:17], v[4:5], 2, s[86:87]
	global_load_dwordx4 v[12:15], v[16:17], off offset:16
	s_nop 0
	global_load_dwordx4 v[16:19], v[16:17], off
	v_ashrrev_i32_e32 v7, 31, v6
	v_lshlrev_b64 v[4:5], 1, v[4:5]
	s_waitcnt vmcnt(1) lgkmcnt(0)
	v_pk_add_f32 v[12:13], v[8:9], v[12:13]
	v_lshlrev_b64 v[8:9], 10, v[6:7]
	s_waitcnt vmcnt(0)
	v_pk_add_f32 v[16:17], v[0:1], v[16:17]
	v_lshl_add_u64 v[0:1], s[4:5], 0, v[8:9]
	v_lshl_add_u64 v[0:1], v[0:1], 0, v[4:5]
	v_add_co_u32_e32 v0, vcc, s20, v0
	v_lshl_add_u64 v[8:9], s[18:19], 0, v[8:9]
	s_nop 0
	v_addc_co_u32_e32 v1, vcc, -1, v1, vcc
	v_pk_add_f32 v[18:19], v[2:3], v[18:19]
	global_load_dwordx4 v[0:3], v[0:1], off
	v_lshl_add_u64 v[8:9], v[8:9], 0, v[4:5]
	v_pk_add_f32 v[14:15], v[10:11], v[14:15]
	global_load_dwordx4 v[8:11], v[8:9], off
	v_mul_f32_e32 v16, 0xbfb8aa3b, v16
	v_mul_f32_e32 v17, 0xbfb8aa3b, v17
	v_exp_f32_e32 v16, v16
	v_exp_f32_e32 v17, v17
	v_lshlrev_b64 v[6:7], 11, v[6:7]
	v_lshl_add_u64 v[6:7], s[40:41], 0, v[6:7]
	v_add_f32_e32 v16, 1.0, v16
	v_add_f32_e32 v17, 1.0, v17
	v_rcp_f32_e32 v16, v16
	v_rcp_f32_e32 v17, v17
	v_lshl_add_u64 v[4:5], v[6:7], 0, v[4:5]
	s_waitcnt vmcnt(1)
	v_lshlrev_b32_e32 v20, 16, v0
	v_and_b32_e32 v21, 0xffff0000, v0
	v_pk_mul_f32 v[16:17], v[16:17], v[20:21]
	s_waitcnt vmcnt(0)
	v_lshlrev_b32_e32 v20, 16, v8
	v_and_b32_e32 v21, 0xffff0000, v8
	v_mul_f32_e32 v8, 0xbfb8aa3b, v18
	v_exp_f32_e32 v8, v8
	v_pk_mul_f32 v[16:17], v[16:17], v[20:21]
	v_lshlrev_b32_e32 v18, 16, v1
	v_cvt_pk_bf16_f32 v0, v16, v17
	v_add_f32_e32 v8, 1.0, v8
	v_rcp_f32_e32 v16, v8
	v_mul_f32_e32 v8, 0xbfb8aa3b, v19
	v_exp_f32_e32 v8, v8
	v_and_b32_e32 v19, 0xffff0000, v1
	v_add_f32_e32 v8, 1.0, v8
	v_rcp_f32_e32 v17, v8
	v_lshlrev_b32_e32 v8, 16, v9
	v_and_b32_e32 v9, 0xffff0000, v9
	v_pk_mul_f32 v[16:17], v[16:17], v[18:19]
	s_nop 0
	v_pk_mul_f32 v[8:9], v[16:17], v[8:9]
	s_nop 0
	v_cvt_pk_bf16_f32 v1, v8, v9
	v_mul_f32_e32 v8, 0xbfb8aa3b, v12
	v_mul_f32_e32 v9, 0xbfb8aa3b, v13
	v_exp_f32_e32 v8, v8
	v_exp_f32_e32 v9, v9
	v_lshlrev_b32_e32 v12, 16, v2
	v_and_b32_e32 v13, 0xffff0000, v2
	v_add_f32_e32 v8, 1.0, v8
	v_add_f32_e32 v9, 1.0, v9
	v_rcp_f32_e32 v8, v8
	v_rcp_f32_e32 v9, v9
	s_nop 0
	v_pk_mul_f32 v[8:9], v[8:9], v[12:13]
	v_lshlrev_b32_e32 v12, 16, v10
	v_and_b32_e32 v13, 0xffff0000, v10
	v_pk_mul_f32 v[8:9], v[8:9], v[12:13]
	v_lshlrev_b32_e32 v12, 16, v3
	v_cvt_pk_bf16_f32 v2, v8, v9
	v_mul_f32_e32 v8, 0xbfb8aa3b, v14
	v_mul_f32_e32 v9, 0xbfb8aa3b, v15
	v_exp_f32_e32 v8, v8
	v_exp_f32_e32 v9, v9
	v_and_b32_e32 v13, 0xffff0000, v3
	v_lshlrev_b32_e32 v10, 16, v11
	v_add_f32_e32 v8, 1.0, v8
	v_add_f32_e32 v9, 1.0, v9
	v_rcp_f32_e32 v8, v8
	v_rcp_f32_e32 v9, v9
	v_and_b32_e32 v11, 0xffff0000, v11
	v_pk_mul_f32 v[8:9], v[8:9], v[12:13]
	s_nop 0
	v_pk_mul_f32 v[8:9], v[8:9], v[10:11]
	s_nop 0
	v_cvt_pk_bf16_f32 v3, v8, v9
	global_store_dwordx4 v[4:5], v[0:3], off
	s_branch .LBB0_687

; #define LAS __attribute__((address_space(3)))
; __device__ __forceinline__ int fresh_tid() { int t = threadIdx.x; asm volatile("" : "+v"(t)); return t; }
; template <class BRow>
; __device__ __forceinline__ void skinny32(LAS float* Cs, const bf16_t* A, int lda, const bf16_t* Bt, int ldb, int NC, int K, const BRow& brow) {
;     ...
;     for (int ct = wave; ct < nct; ct += NWAVES) {
;         f32x4 acc0 = {0.f, 0.f, 0.f, 0.f}, acc1 = acc0;
;         const bf16_t* ap = A + (size_t)fr * lda + fq * 8; const bf16_t* bp = Bt + (size_t)(brow(ct) + fr) * ldb + fq * 8;
;         bf16x8 a0[8], a1[8], b[8];
; #pragma unroll
;         for (int i = 0; i < 8; ++i) { a0[i] = *(const bf16x8*)(ap + 32 * i); a1[i] = *(const bf16x8*)(ap + (size_t)16 * lda + 32 * i); b[i] = *(const bf16x8*)(bp + 32 * i); }
; #pragma unroll 1
;         for (int k0 = 0; k0 < K; k0 += 256) {
;             bf16x8 n0[8], n1[8], nb[8];
;             const int kn = (k0 + 256 < K) ? k0 + 256 : k0;
; #pragma unroll
;             for (int i = 0; i < 8; ++i) { n0[i] = *(const bf16x8*)(ap + kn + 32 * i); n1[i] = *(const bf16x8*)(ap + (size_t)16 * lda + kn + 32 * i); nb[i] = *(const bf16x8*)(bp + kn + 32 * i); }
; #pragma unroll
;             for (int i = 0; i < 8; ++i) { acc0 = __builtin_amdgcn_mfma_f32_16x16x32_bf16(b[i], a0[i], acc0, 0, 0, 0); acc1 = __builtin_amdgcn_mfma_f32_16x16x32_bf16(b[i], a1[i], acc1, 0, 0, 0); }
; #pragma unroll
;             for (int i = 0; i < 8; ++i) { a0[i] = n0[i]; a1[i] = n1[i]; b[i] = nb[i]; }
;         }
;         *(LAS f32x4*)(Cs + fr * ldc + ct * 16 + 4 * fq) = acc0; *(LAS f32x4*)(Cs + (16 + fr) * ldc + ct * 16 + 4 * fq) = acc1;
; __global__ void __launch_bounds__(NTHR, 2) hymba_fwd(Params P) {
;     ...
;     for (int it = blk; it < 256; it += G) {
;         const int mb = it & 15, ns = it >> 4;
;         LAS float* Cs = (LAS float*)lds; constexpr int ldc = 68;
;         __syncthreads();
;         skinny32(Cs, MX + (size_t)(PT + 32 * mb) * DM, DM, WOUT, DM, 64, DM, [&](int ct) { return 64 * ns + 16 * ct; });
;         const int tid = fresh_tid();
.LBB0_887:
	s_lshl_b32 s4, s52, 5
	v_mov_b32_e32 v0, v208
	s_barrier
	s_and_b32 s64, s4, 0x1e0
	s_ashr_i32 s53, s52, 4
	s_lshl_b32 s4, s64, 11
	s_add_u32 s66, s92, s4
	s_addc_u32 s67, s93, 0
	s_add_u32 s66, s66, 0x9800000
	s_addc_u32 s67, s67, 0
	v_mov_b32_e32 v0, v208
	v_lshrrev_b32_e32 v1, 4, v0
	v_and_b32_e32 v2, 15, v0
	v_readfirstlane_b32 s62, v0
	v_lshlrev_b32_e32 v6, 4, v2
	v_lshl_add_u32 v6, v1, 11, v6
	s_nop 3
	s_ashr_i32 s62, s62, 6
	global_load_dwordx4 v[32:35], v6, s[66:67]
	global_load_dwordx4 v[36:39], v6, s[66:67] offset:256
	global_load_dwordx4 v[40:43], v6, s[66:67] offset:512
	global_load_dwordx4 v[44:47], v6, s[66:67] offset:768
	global_load_dwordx4 v[48:51], v6, s[66:67] offset:1024
	global_load_dwordx4 v[60:63], v6, s[66:67] offset:1280
	global_load_dwordx4 v[64:67], v6, s[66:67] offset:1536
	global_load_dwordx4 v[68:71], v6, s[66:67] offset:1792
	v_mul_u32_u24_e32 v7, 2064, v1
	v_lshl_add_u32 v7, v2, 4, v7
	v_add_u32_e32 v7, 0x8000, v7
	s_cmp_gt_i32 s62, 3
	s_cbranch_scc1 .Lmy_sk5_helper
	v_and_b32_e32 v8, 63, v0
	v_and_b32_e32 v9, 15, v8
	v_lshrrev_b32_e32 v10, 4, v8
	v_lshlrev_b32_e32 v3, 4, v10
	v_lshl_add_u32 v3, v9, 11, v3
	v_mul_u32_u24_e32 v4, 2064, v9
	v_lshl_add_u32 v4, v10, 4, v4
	v_add_u32_e32 v4, 0x8000, v4
	v_mul_u32_u24_e32 v5, 0x110, v9
	v_lshl_add_u32 v5, v10, 4, v5
	s_lshl_b32 s63, s62, 6
	v_add_u32_e32 v5, s63, v5
	s_lshl_b32 s4, s53, 6
	s_lshl_b32 s14, s62, 4
	s_add_i32 s4, s4, s14
	s_lshl_b32 s4, s4, 11
	s_add_u32 s68, s96, s4
	s_addc_u32 s69, s97, 0
	v_mov_b32_e32 v16, 0
	v_mov_b32_e32 v17, 0
	v_mov_b32_e32 v18, 0
	v_mov_b32_e32 v19, 0
	v_mov_b32_e32 v20, 0
	v_mov_b32_e32 v21, 0
	v_mov_b32_e32 v22, 0
	v_mov_b32_e32 v23, 0
	global_load_dwordx4 v[124:127], v3, s[68:69]
	global_load_dwordx4 v[128:131], v3, s[68:69] offset:64
	global_load_dwordx4 v[132:135], v3, s[68:69] offset:128
	global_load_dwordx4 v[136:139], v3, s[68:69] offset:192
	global_load_dwordx4 v[140:143], v3, s[68:69] offset:256
	global_load_dwordx4 v[144:147], v3, s[68:69] offset:320
	global_load_dwordx4 v[148:151], v3, s[68:69] offset:384
	global_load_dwordx4 v[152:155], v3, s[68:69] offset:448
	global_load_dwordx4 v[156:159], v3, s[68:69] offset:512
	global_load_dwordx4 v[160:163], v3, s[68:69] offset:576
	global_load_dwordx4 v[164:167], v3, s[68:69] offset:640
	global_load_dwordx4 v[168:171], v3, s[68:69] offset:704
	global_load_dwordx4 v[172:175], v3, s[68:69] offset:768
	global_load_dwordx4 v[176:179], v3, s[68:69] offset:832
	global_load_dwordx4 v[180:183], v3, s[68:69] offset:896
	global_load_dwordx4 v[184:187], v3, s[68:69] offset:960
	global_load_dwordx4 v[188:191], v3, s[68:69] offset:1024
	global_load_dwordx4 v[192:195], v3, s[68:69] offset:1088
	global_load_dwordx4 v[196:199], v3, s[68:69] offset:1152
	global_load_dwordx4 v[212:215], v3, s[68:69] offset:1216
	global_load_dwordx4 v[216:219], v3, s[68:69] offset:1280
	global_load_dwordx4 v[220:223], v3, s[68:69] offset:1344
	global_load_dwordx4 v[224:227], v3, s[68:69] offset:1408
	global_load_dwordx4 v[228:231], v3, s[68:69] offset:1472
	global_load_dwordx4 v[232:235], v3, s[68:69] offset:1536
	global_load_dwordx4 v[236:239], v3, s[68:69] offset:1600
	global_load_dwordx4 v[240:243], v3, s[68:69] offset:1664
	global_load_dwordx4 v[244:247], v3, s[68:69] offset:1728
	global_load_dwordx4 v[248:251], v3, s[68:69] offset:1792
	global_load_dwordx4 v[100:103], v3, s[68:69] offset:1856
	global_load_dwordx4 v[104:107], v3, s[68:69] offset:1920
	global_load_dwordx4 v[108:111], v3, s[68:69] offset:1984
	s_waitcnt vmcnt(32)
	ds_write_b128 v7, v[32:35]
	ds_write_b128 v7, v[36:39] offset:256
	ds_write_b128 v7, v[40:43] offset:512
	ds_write_b128 v7, v[44:47] offset:768
	ds_write_b128 v7, v[48:51] offset:1024
	ds_write_b128 v7, v[60:63] offset:1280
	ds_write_b128 v7, v[64:67] offset:1536
	ds_write_b128 v7, v[68:71] offset:1792
	s_waitcnt lgkmcnt(0)
	s_barrier
	ds_read_b128 v[76:79], v4 offset:0
	ds_read_b128 v[80:83], v4 offset:33024
	ds_read_b128 v[84:87], v4 offset:64
	ds_read_b128 v[88:91], v4 offset:33088
	ds_read_b128 v[92:95], v4 offset:128
	ds_read_b128 v[96:99], v4 offset:33152
	s_waitcnt vmcnt(31) lgkmcnt(4)
	v_mfma_f32_16x16x32_bf16 v[16:19], v[124:127], v[76:79], v[16:19]
	v_mfma_f32_16x16x32_bf16 v[20:23], v[124:127], v[80:83], v[20:23]
	ds_read_b128 v[76:79], v4 offset:192
	ds_read_b128 v[80:83], v4 offset:33216
	s_waitcnt vmcnt(30) lgkmcnt(4)
	v_mfma_f32_16x16x32_bf16 v[16:19], v[128:131], v[84:87], v[16:19]
	v_mfma_f32_16x16x32_bf16 v[20:23], v[128:131], v[88:91], v[20:23]
	ds_read_b128 v[84:87], v4 offset:256
	ds_read_b128 v[88:91], v4 offset:33280
	s_waitcnt vmcnt(29) lgkmcnt(4)
	v_mfma_f32_16x16x32_bf16 v[16:19], v[132:135], v[92:95], v[16:19]
	v_mfma_f32_16x16x32_bf16 v[20:23], v[132:135], v[96:99], v[20:23]
	ds_read_b128 v[92:95], v4 offset:320
	ds_read_b128 v[96:99], v4 offset:33344
	s_waitcnt vmcnt(28) lgkmcnt(4)
	v_mfma_f32_16x16x32_bf16 v[16:19], v[136:139], v[76:79], v[16:19]
	v_mfma_f32_16x16x32_bf16 v[20:23], v[136:139], v[80:83], v[20:23]
	ds_read_b128 v[76:79], v4 offset:384
	ds_read_b128 v[80:83], v4 offset:33408
	s_waitcnt vmcnt(27) lgkmcnt(4)
	v_mfma_f32_16x16x32_bf16 v[16:19], v[140:143], v[84:87], v[16:19]
	v_mfma_f32_16x16x32_bf16 v[20:23], v[140:143], v[88:91], v[20:23]
	ds_read_b128 v[84:87], v4 offset:448
	ds_read_b128 v[88:91], v4 offset:33472
	s_waitcnt vmcnt(26) lgkmcnt(4)
	v_mfma_f32_16x16x32_bf16 v[16:19], v[144:147], v[92:95], v[16:19]
	v_mfma_f32_16x16x32_bf16 v[20:23], v[144:147], v[96:99], v[20:23]
	ds_read_b128 v[92:95], v4 offset:512
	ds_read_b128 v[96:99], v4 offset:33536
	s_waitcnt vmcnt(25) lgkmcnt(4)
; #define LAS __attribute__((address_space(3)))
; template <class BRow>
; __device__ __forceinline__ void skinny32(LAS float* Cs, const bf16_t* A, int lda, const bf16_t* Bt, int ldb, int NC, int K, const BRow& brow) {
;     ...
;             for (int i = 0; i < 8; ++i) { n0[i] = *(const bf16x8*)(ap + kn + 32 * i); n1[i] = *(const bf16x8*)(ap + (size_t)16 * lda + kn + 32 * i); nb[i] = *(const bf16x8*)(bp + kn + 32 * i); }
; #pragma unroll
;             for (int i = 0; i < 8; ++i) { acc0 = __builtin_amdgcn_mfma_f32_16x16x32_bf16(b[i], a0[i], acc0, 0, 0, 0); acc1 = __builtin_amdgcn_mfma_f32_16x16x32_bf16(b[i], a1[i], acc1, 0, 0, 0); }
; #pragma unroll
;             for (int i = 0; i < 8; ++i) { a0[i] = n0[i]; a1[i] = n1[i]; b[i] = nb[i]; }
;         }
;         *(LAS f32x4*)(Cs + fr * ldc + ct * 16 + 4 * fq) = acc0; *(LAS f32x4*)(Cs + (16 + fr) * ldc + ct * 16 + 4 * fq) = acc1;
	v_mfma_f32_16x16x32_bf16 v[16:19], v[148:151], v[76:79], v[16:19]
	v_mfma_f32_16x16x32_bf16 v[20:23], v[148:151], v[80:83], v[20:23]
	ds_read_b128 v[76:79], v4 offset:576
	ds_read_b128 v[80:83], v4 offset:33600
	s_waitcnt vmcnt(24) lgkmcnt(4)
	v_mfma_f32_16x16x32_bf16 v[16:19], v[152:155], v[84:87], v[16:19]
	v_mfma_f32_16x16x32_bf16 v[20:23], v[152:155], v[88:91], v[20:23]
	ds_read_b128 v[84:87], v4 offset:640
	ds_read_b128 v[88:91], v4 offset:33664
	s_waitcnt vmcnt(23) lgkmcnt(4)
	v_mfma_f32_16x16x32_bf16 v[16:19], v[156:159], v[92:95], v[16:19]
	v_mfma_f32_16x16x32_bf16 v[20:23], v[156:159], v[96:99], v[20:23]
	ds_read_b128 v[92:95], v4 offset:704
	ds_read_b128 v[96:99], v4 offset:33728
	s_waitcnt vmcnt(22) lgkmcnt(4)
	v_mfma_f32_16x16x32_bf16 v[16:19], v[160:163], v[76:79], v[16:19]
	v_mfma_f32_16x16x32_bf16 v[20:23], v[160:163], v[80:83], v[20:23]
	ds_read_b128 v[76:79], v4 offset:768
	ds_read_b128 v[80:83], v4 offset:33792
	s_waitcnt vmcnt(21) lgkmcnt(4)
	v_mfma_f32_16x16x32_bf16 v[16:19], v[164:167], v[84:87], v[16:19]
	v_mfma_f32_16x16x32_bf16 v[20:23], v[164:167], v[88:91], v[20:23]
	ds_read_b128 v[84:87], v4 offset:832
	ds_read_b128 v[88:91], v4 offset:33856
	s_waitcnt vmcnt(20) lgkmcnt(4)
	v_mfma_f32_16x16x32_bf16 v[16:19], v[168:171], v[92:95], v[16:19]
	v_mfma_f32_16x16x32_bf16 v[20:23], v[168:171], v[96:99], v[20:23]
	ds_read_b128 v[92:95], v4 offset:896
	ds_read_b128 v[96:99], v4 offset:33920
	s_waitcnt vmcnt(19) lgkmcnt(4)
	v_mfma_f32_16x16x32_bf16 v[16:19], v[172:175], v[76:79], v[16:19]
	v_mfma_f32_16x16x32_bf16 v[20:23], v[172:175], v[80:83], v[20:23]
	ds_read_b128 v[76:79], v4 offset:960
	ds_read_b128 v[80:83], v4 offset:33984
	s_waitcnt vmcnt(18) lgkmcnt(4)
	v_mfma_f32_16x16x32_bf16 v[16:19], v[176:179], v[84:87], v[16:19]
	v_mfma_f32_16x16x32_bf16 v[20:23], v[176:179], v[88:91], v[20:23]
	ds_read_b128 v[84:87], v4 offset:1024
	ds_read_b128 v[88:91], v4 offset:34048
	s_waitcnt vmcnt(17) lgkmcnt(4)
	v_mfma_f32_16x16x32_bf16 v[16:19], v[180:183], v[92:95], v[16:19]
	v_mfma_f32_16x16x32_bf16 v[20:23], v[180:183], v[96:99], v[20:23]
	ds_read_b128 v[92:95], v4 offset:1088
	ds_read_b128 v[96:99], v4 offset:34112
	s_waitcnt vmcnt(16) lgkmcnt(4)
	v_mfma_f32_16x16x32_bf16 v[16:19], v[184:187], v[76:79], v[16:19]
	v_mfma_f32_16x16x32_bf16 v[20:23], v[184:187], v[80:83], v[20:23]
	ds_read_b128 v[76:79], v4 offset:1152
	ds_read_b128 v[80:83], v4 offset:34176
	s_waitcnt vmcnt(15) lgkmcnt(4)
	v_mfma_f32_16x16x32_bf16 v[16:19], v[188:191], v[84:87], v[16:19]
	v_mfma_f32_16x16x32_bf16 v[20:23], v[188:191], v[88:91], v[20:23]
	ds_read_b128 v[84:87], v4 offset:1216
	ds_read_b128 v[88:91], v4 offset:34240
	s_waitcnt vmcnt(14) lgkmcnt(4)
	v_mfma_f32_16x16x32_bf16 v[16:19], v[192:195], v[92:95], v[16:19]
	v_mfma_f32_16x16x32_bf16 v[20:23], v[192:195], v[96:99], v[20:23]
	ds_read_b128 v[92:95], v4 offset:1280
	ds_read_b128 v[96:99], v4 offset:34304
	s_waitcnt vmcnt(13) lgkmcnt(4)
	v_mfma_f32_16x16x32_bf16 v[16:19], v[196:199], v[76:79], v[16:19]
	v_mfma_f32_16x16x32_bf16 v[20:23], v[196:199], v[80:83], v[20:23]
	ds_read_b128 v[76:79], v4 offset:1344
	ds_read_b128 v[80:83], v4 offset:34368
	s_waitcnt vmcnt(12) lgkmcnt(4)
	v_mfma_f32_16x16x32_bf16 v[16:19], v[212:215], v[84:87], v[16:19]
	v_mfma_f32_16x16x32_bf16 v[20:23], v[212:215], v[88:91], v[20:23]
	ds_read_b128 v[84:87], v4 offset:1408
	ds_read_b128 v[88:91], v4 offset:34432
	s_waitcnt vmcnt(11) lgkmcnt(4)
	v_mfma_f32_16x16x32_bf16 v[16:19], v[216:219], v[92:95], v[16:19]
	v_mfma_f32_16x16x32_bf16 v[20:23], v[216:219], v[96:99], v[20:23]
	ds_read_b128 v[92:95], v4 offset:1472
	ds_read_b128 v[96:99], v4 offset:34496
	s_waitcnt vmcnt(10) lgkmcnt(4)
	v_mfma_f32_16x16x32_bf16 v[16:19], v[220:223], v[76:79], v[16:19]
	v_mfma_f32_16x16x32_bf16 v[20:23], v[220:223], v[80:83], v[20:23]
	ds_read_b128 v[76:79], v4 offset:1536
	ds_read_b128 v[80:83], v4 offset:34560
	s_waitcnt vmcnt(9) lgkmcnt(4)
	v_mfma_f32_16x16x32_bf16 v[16:19], v[224:227], v[84:87], v[16:19]
	v_mfma_f32_16x16x32_bf16 v[20:23], v[224:227], v[88:91], v[20:23]
	ds_read_b128 v[84:87], v4 offset:1600
	ds_read_b128 v[88:91], v4 offset:34624
	s_waitcnt vmcnt(8) lgkmcnt(4)
	v_mfma_f32_16x16x32_bf16 v[16:19], v[228:231], v[92:95], v[16:19]
	v_mfma_f32_16x16x32_bf16 v[20:23], v[228:231], v[96:99], v[20:23]
	ds_read_b128 v[92:95], v4 offset:1664
	ds_read_b128 v[96:99], v4 offset:34688
	s_waitcnt vmcnt(7) lgkmcnt(4)
	v_mfma_f32_16x16x32_bf16 v[16:19], v[232:235], v[76:79], v[16:19]
	v_mfma_f32_16x16x32_bf16 v[20:23], v[232:235], v[80:83], v[20:23]
	ds_read_b128 v[76:79], v4 offset:1728
	ds_read_b128 v[80:83], v4 offset:34752
	s_waitcnt vmcnt(6) lgkmcnt(4)
	v_mfma_f32_16x16x32_bf16 v[16:19], v[236:239], v[84:87], v[16:19]
	v_mfma_f32_16x16x32_bf16 v[20:23], v[236:239], v[88:91], v[20:23]
	ds_read_b128 v[84:87], v4 offset:1792
	ds_read_b128 v[88:91], v4 offset:34816
	s_waitcnt vmcnt(5) lgkmcnt(4)
	v_mfma_f32_16x16x32_bf16 v[16:19], v[240:243], v[92:95], v[16:19]
	v_mfma_f32_16x16x32_bf16 v[20:23], v[240:243], v[96:99], v[20:23]
	ds_read_b128 v[92:95], v4 offset:1856
	ds_read_b128 v[96:99], v4 offset:34880
	s_waitcnt vmcnt(4) lgkmcnt(4)
	v_mfma_f32_16x16x32_bf16 v[16:19], v[244:247], v[76:79], v[16:19]
	v_mfma_f32_16x16x32_bf16 v[20:23], v[244:247], v[80:83], v[20:23]
	ds_read_b128 v[76:79], v4 offset:1920
	ds_read_b128 v[80:83], v4 offset:34944
	s_waitcnt vmcnt(3) lgkmcnt(4)
	v_mfma_f32_16x16x32_bf16 v[16:19], v[248:251], v[84:87], v[16:19]
	v_mfma_f32_16x16x32_bf16 v[20:23], v[248:251], v[88:91], v[20:23]
	ds_read_b128 v[84:87], v4 offset:1984
	ds_read_b128 v[88:91], v4 offset:35008
	s_waitcnt vmcnt(2) lgkmcnt(4)
	v_mfma_f32_16x16x32_bf16 v[16:19], v[100:103], v[92:95], v[16:19]
	v_mfma_f32_16x16x32_bf16 v[20:23], v[100:103], v[96:99], v[20:23]
	s_waitcnt vmcnt(1) lgkmcnt(2)
	v_mfma_f32_16x16x32_bf16 v[16:19], v[104:107], v[76:79], v[16:19]
	v_mfma_f32_16x16x32_bf16 v[20:23], v[104:107], v[80:83], v[20:23]
	s_waitcnt vmcnt(0) lgkmcnt(0)
	v_mfma_f32_16x16x32_bf16 v[16:19], v[108:111], v[84:87], v[16:19]
	v_mfma_f32_16x16x32_bf16 v[20:23], v[108:111], v[88:91], v[20:23]
	s_nop 7
	s_nop 3
	ds_write_b128 v5, v[16:19]
	ds_write_b128 v5, v[20:23] offset:4352
	s_branch .Lmy_sk5_done
; #define LAS __attribute__((address_space(3)))
; __device__ __forceinline__ int fresh_tid() { int t = threadIdx.x; asm volatile("" : "+v"(t)); return t; }
; #define MOD WSP(float, WS_MOD)
; __global__ void __launch_bounds__(NTHR, 2) hymba_fwd(Params P) {
;     ...
;         const int tid = fresh_tid();
;         if (tid < 256) { const int row = tid >> 3, ch = tid & 7, col = 64 * ns + 8 * ch, sidx = 32 * mb + row; const float* gt = MOD + (size_t)(8 + (sidx >> 6)) * 3072 + 2048 + col;
;             const float* xr = P.x_sample + (size_t)sidx * DM + col; float* yr = out + O_YS + (size_t)sidx * DM + col;
;             *(f32x4*)yr = *(const f32x4*)xr + *(const f32x4*)gt * *(const LAS f32x4*)(Cs + row * ldc + 8 * ch);
;             *(f32x4*)(yr + 4) = *(const f32x4*)(xr + 4) + *(const f32x4*)(gt + 4) * *(const LAS f32x4*)(Cs + row * ldc + 8 * ch + 4); }
;         __syncthreads();
.Lmy_sk5_helper:
	s_waitcnt vmcnt(0)
	ds_write_b128 v7, v[32:35]
	ds_write_b128 v7, v[36:39] offset:256
	ds_write_b128 v7, v[40:43] offset:512
	ds_write_b128 v7, v[44:47] offset:768
	ds_write_b128 v7, v[48:51] offset:1024
	ds_write_b128 v7, v[60:63] offset:1280
	ds_write_b128 v7, v[64:67] offset:1536
	ds_write_b128 v7, v[68:71] offset:1792
	s_waitcnt lgkmcnt(0)
	s_barrier
.Lmy_sk5_done:
.LBB0_892:
	v_mov_b32_e32 v0, v208
	s_waitcnt lgkmcnt(0)
	s_barrier
	s_nop 0
	v_cmp_gt_i32_e32 vcc, s21, v0
	s_and_saveexec_b64 s[62:63], vcc
	s_cbranch_execz .LBB0_886
	v_ashrrev_i32_e32 v8, 3, v0
	v_lshlrev_b32_e32 v0, 3, v0
	v_add_u32_e32 v2, s64, v8
	v_and_b32_e32 v9, 56, v0
	v_ashrrev_i32_e32 v1, 6, v2
	v_lshl_or_b32 v0, s53, 6, v9
	v_add_u32_e32 v1, 8, v1
	v_mov_b64_e32 v[4:5], s[92:93]
	v_mad_i64_i32 v[4:5], s[64:65], v1, s50, v[4:5]
	v_ashrrev_i32_e32 v1, 31, v0
	v_lshlrev_b64 v[16:17], 2, v[0:1]
	v_ashrrev_i32_e32 v3, 31, v2
	v_lshl_add_u64 v[18:19], v[4:5], 0, v[16:17]
	v_lshlrev_b64 v[12:13], 12, v[2:3]
	v_lshl_add_u64 v[0:1], s[38:39], 0, v[12:13]
	v_add_co_u32_e32 v4, vcc, s51, v18
	v_lshl_add_u64 v[20:21], v[0:1], 0, v[16:17]
	s_nop 0
	v_addc_co_u32_e32 v5, vcc, 0, v19, vcc
	global_load_dwordx4 v[0:3], v[20:21], off
	v_mul_lo_u32 v8, v8, s17
	global_load_dwordx4 v[4:7], v[4:5], off
	v_lshlrev_b32_e32 v9, 2, v9
	v_add3_u32 v14, 0, v8, v9
	ds_read_b128 v[8:11], v14
	v_lshl_add_u64 v[22:23], s[0:1], 0, v[12:13]
	v_lshl_add_u64 v[16:17], v[22:23], 0, v[16:17]
	ds_read_b128 v[12:15], v14 offset:16
	v_lshl_add_u64 v[18:19], v[18:19], 0, s[60:61]
	s_waitcnt vmcnt(0) lgkmcnt(1)
	v_pk_fma_f32 v[2:3], v[6:7], v[10:11], v[2:3]
	v_pk_fma_f32 v[0:1], v[4:5], v[8:9], v[0:1]
	global_store_dwordx4 v[16:17], v[0:3], off
	global_load_dwordx4 v[0:3], v[20:21], off offset:16
	s_nop 0
	global_load_dwordx4 v[4:7], v[18:19], off offset:16
	s_waitcnt vmcnt(0) lgkmcnt(0)
	v_pk_fma_f32 v[2:3], v[6:7], v[14:15], v[2:3]
	v_pk_fma_f32 v[0:1], v[4:5], v[12:13], v[0:1]
	global_store_dwordx4 v[16:17], v[0:3], off offset:16
	s_branch .LBB0_886
